# attention fast path: s_setprio 1 around the QK and PV MFMA sections (timing-only)
# baseline (speedup 1.0000x reference)
.Lattn_fast:
	v_add_u32_e32 v241, s4, v159
	v_add_u32_e32 v201, v241, v161
	ds_read_b128 v[220:223], v201
	ds_read_b128 v[224:227], v201 offset:64
	ds_read_b128 v[228:231], v201 offset:2304
	ds_read_b128 v[232:235], v201 offset:2368
	ds_read_b128 v[236:239], v201 offset:4608
	ds_read_b128 v[252:255], v201 offset:4672
	s_setprio 1
	s_waitcnt lgkmcnt(4)
	v_mfma_f32_16x16x32_bf16 v[40:43], v[220:223], v[16:19], 0
	v_mfma_f32_16x16x32_bf16 v[40:43], v[224:227], v[20:23], v[40:43]
	ds_read_b128 v[220:223], v201 offset:6912
	ds_read_b128 v[224:227], v201 offset:6976
	s_waitcnt lgkmcnt(4)
	v_mfma_f32_16x16x32_bf16 v[44:47], v[228:231], v[16:19], 0
	v_mfma_f32_16x16x32_bf16 v[44:47], v[232:235], v[20:23], v[44:47]
	ds_read_b128 v[228:231], v201 offset:9216
	ds_read_b128 v[232:235], v201 offset:9280
	s_waitcnt lgkmcnt(4)
	v_mfma_f32_16x16x32_bf16 v[48:51], v[236:239], v[16:19], 0
	v_mfma_f32_16x16x32_bf16 v[48:51], v[252:255], v[20:23], v[48:51]
	ds_read_b128 v[236:239], v201 offset:11520
	ds_read_b128 v[252:255], v201 offset:11584
	s_waitcnt lgkmcnt(4)
	v_mfma_f32_16x16x32_bf16 v[52:55], v[220:223], v[16:19], 0
	v_mfma_f32_16x16x32_bf16 v[52:55], v[224:227], v[20:23], v[52:55]
	ds_read_b128 v[220:223], v201 offset:13824
	ds_read_b128 v[224:227], v201 offset:13888
	s_waitcnt lgkmcnt(4)
	v_mfma_f32_16x16x32_bf16 v[56:59], v[228:231], v[16:19], 0
	v_mfma_f32_16x16x32_bf16 v[56:59], v[232:235], v[20:23], v[56:59]
	ds_read_b128 v[228:231], v201 offset:16128
	ds_read_b128 v[232:235], v201 offset:16192
	s_waitcnt lgkmcnt(4)
	v_mfma_f32_16x16x32_bf16 v[60:63], v[236:239], v[16:19], 0
	v_mfma_f32_16x16x32_bf16 v[60:63], v[252:255], v[20:23], v[60:63]
	s_waitcnt lgkmcnt(2)
	v_mfma_f32_16x16x32_bf16 v[64:67], v[220:223], v[16:19], 0
	v_mfma_f32_16x16x32_bf16 v[64:67], v[224:227], v[20:23], v[64:67]
	s_waitcnt lgkmcnt(0)
	v_mfma_f32_16x16x32_bf16 v[68:71], v[228:231], v[16:19], 0
	v_mfma_f32_16x16x32_bf16 v[68:71], v[232:235], v[20:23], v[68:71]
	s_setprio 0
	s_nop 7
	v_max3_f32 v200, v40, v41, s68
	v_max3_f32 v202, v42, v43, s68
	v_max3_f32 v200, v200, v44, v45
	v_max3_f32 v202, v202, v46, v47
	v_max3_f32 v200, v200, v48, v49
	v_max3_f32 v202, v202, v50, v51
	v_max3_f32 v200, v200, v52, v53
	v_max3_f32 v202, v202, v54, v55
	v_max3_f32 v200, v200, v56, v57
	v_max3_f32 v202, v202, v58, v59
	v_max3_f32 v200, v200, v60, v61
	v_max3_f32 v202, v202, v62, v63
	v_max3_f32 v200, v200, v64, v65
	v_max3_f32 v202, v202, v66, v67
	v_max3_f32 v200, v200, v68, v69
	v_max3_f32 v202, v202, v70, v71
	v_max_f32_e32 v200, v200, v202
	v_max_f32_e32 v151, v200, v200
	v_mov_b32_e32 v72, v151
	s_waitcnt lgkmcnt(0)
	s_nop 1
	v_permlane16_swap_b32_e32 v72, v151
	v_max_f32_e32 v72, v151, v72
	v_mov_b32_e32 v151, v72
	s_nop 1
	v_permlane32_swap_b32_e32 v151, v72
	v_max3_f32 v151, v153, v72, v151
	v_sub_f32_e32 v72, v153, v151
	v_exp_f32_e32 v72, v72
	v_sub_f32_e32 v40, v40, v151
	v_sub_f32_e32 v41, v41, v151
	v_sub_f32_e32 v42, v42, v151
	v_sub_f32_e32 v43, v43, v151
	v_sub_f32_e32 v44, v44, v151
	v_sub_f32_e32 v45, v45, v151
	v_sub_f32_e32 v46, v46, v151
	v_sub_f32_e32 v47, v47, v151
	v_sub_f32_e32 v48, v48, v151
	v_sub_f32_e32 v49, v49, v151
	v_sub_f32_e32 v50, v50, v151
	v_sub_f32_e32 v51, v51, v151
	v_sub_f32_e32 v52, v52, v151
	v_sub_f32_e32 v53, v53, v151
	v_sub_f32_e32 v54, v54, v151
	v_sub_f32_e32 v55, v55, v151
	v_sub_f32_e32 v56, v56, v151
	v_sub_f32_e32 v57, v57, v151
	v_sub_f32_e32 v58, v58, v151
	v_sub_f32_e32 v59, v59, v151
	v_sub_f32_e32 v60, v60, v151
	v_sub_f32_e32 v61, v61, v151
	v_sub_f32_e32 v62, v62, v151
	v_sub_f32_e32 v63, v63, v151
	v_sub_f32_e32 v64, v64, v151
	v_sub_f32_e32 v65, v65, v151
	v_sub_f32_e32 v66, v66, v151
	v_sub_f32_e32 v67, v67, v151
	v_sub_f32_e32 v68, v68, v151
	v_sub_f32_e32 v69, v69, v151
	v_sub_f32_e32 v70, v70, v151
	v_sub_f32_e32 v71, v71, v151
	v_mul_f32_e32 v149, v149, v72
	v_exp_f32_e32 v40, v40
	v_exp_f32_e32 v41, v41
	v_exp_f32_e32 v42, v42
	v_exp_f32_e32 v43, v43
	v_exp_f32_e32 v44, v44
	v_exp_f32_e32 v45, v45
	v_exp_f32_e32 v46, v46
	v_exp_f32_e32 v47, v47
	v_exp_f32_e32 v48, v48
	v_exp_f32_e32 v49, v49
	v_exp_f32_e32 v50, v50
	v_exp_f32_e32 v51, v51
	v_exp_f32_e32 v52, v52
	v_exp_f32_e32 v53, v53
	v_exp_f32_e32 v54, v54
	v_exp_f32_e32 v55, v55
	v_exp_f32_e32 v56, v56
	v_exp_f32_e32 v57, v57
	v_exp_f32_e32 v58, v58
	v_exp_f32_e32 v59, v59
	v_exp_f32_e32 v60, v60
	v_exp_f32_e32 v61, v61
	v_exp_f32_e32 v62, v62
	v_exp_f32_e32 v63, v63
	v_exp_f32_e32 v64, v64
	v_exp_f32_e32 v65, v65
	v_exp_f32_e32 v66, v66
	v_exp_f32_e32 v67, v67
	v_exp_f32_e32 v68, v68
	v_exp_f32_e32 v69, v69
	v_exp_f32_e32 v70, v70
	v_exp_f32_e32 v71, v71
	v_pk_mul_f32 v[38:39], v[38:39], v[72:73] op_sel_hi:[1,0]
	v_pk_mul_f32 v[36:37], v[36:37], v[72:73] op_sel_hi:[1,0]
	v_pk_mul_f32 v[34:35], v[34:35], v[72:73] op_sel_hi:[1,0]
	v_pk_mul_f32 v[32:33], v[32:33], v[72:73] op_sel_hi:[1,0]
	v_pk_mul_f32 v[30:31], v[30:31], v[72:73] op_sel_hi:[1,0]
	v_pk_mul_f32 v[28:29], v[28:29], v[72:73] op_sel_hi:[1,0]
	v_pk_mul_f32 v[26:27], v[26:27], v[72:73] op_sel_hi:[1,0]
	v_pk_mul_f32 v[24:25], v[24:25], v[72:73] op_sel_hi:[1,0]
	v_lshl_add_u32 v241, v160, 1, s38
	v_add_u32_e32 v241, v241, v162
	ds_read_b64_tr_b16 v[220:221], v241
	ds_read_b64_tr_b16 v[222:223], v241 offset:2304
	ds_read_b64_tr_b16 v[224:225], v241 offset:32
	ds_read_b64_tr_b16 v[226:227], v241 offset:2336
	ds_read_b64_tr_b16 v[228:229], v241 offset:64
	ds_read_b64_tr_b16 v[230:231], v241 offset:2368
	ds_read_b64_tr_b16 v[232:233], v241 offset:96
	ds_read_b64_tr_b16 v[234:235], v241 offset:2400
	ds_read_b64_tr_b16 v[236:237], v241 offset:4608
	ds_read_b64_tr_b16 v[238:239], v241 offset:6912
	ds_read_b64_tr_b16 v[252:253], v241 offset:4640
	ds_read_b64_tr_b16 v[254:255], v241 offset:6944
	v_add_f32_e32 v149, v40, v149
	v_add_f32_e32 v149, v41, v149
	v_add_f32_e32 v149, v42, v149
	v_add_f32_e32 v149, v43, v149
	v_add_f32_e32 v149, v44, v149
	v_add_f32_e32 v149, v45, v149
	v_add_f32_e32 v149, v46, v149
	v_add_f32_e32 v149, v47, v149
	v_add_f32_e32 v149, v48, v149
	v_add_f32_e32 v149, v49, v149
	v_add_f32_e32 v149, v50, v149
	v_add_f32_e32 v149, v51, v149
	v_add_f32_e32 v149, v52, v149
	v_add_f32_e32 v149, v53, v149
	v_add_f32_e32 v149, v54, v149
	v_add_f32_e32 v149, v55, v149
	v_add_f32_e32 v149, v56, v149
	v_add_f32_e32 v149, v57, v149
	v_add_f32_e32 v149, v58, v149
	v_add_f32_e32 v149, v59, v149
	v_add_f32_e32 v149, v60, v149
	v_add_f32_e32 v149, v61, v149
	v_add_f32_e32 v149, v62, v149
	v_add_f32_e32 v149, v63, v149
	v_add_f32_e32 v149, v64, v149
	v_add_f32_e32 v149, v65, v149
	v_add_f32_e32 v149, v66, v149
	v_add_f32_e32 v149, v67, v149
	v_add_f32_e32 v149, v68, v149
	v_add_f32_e32 v149, v69, v149
	v_add_f32_e32 v149, v70, v149
	v_add_f32_e32 v149, v71, v149
	v_cvt_pk_bf16_f32 v40, v40, v41
	v_cvt_pk_bf16_f32 v41, v42, v43
	v_cvt_pk_bf16_f32 v42, v44, v45
	v_cvt_pk_bf16_f32 v43, v46, v47
	v_cvt_pk_bf16_f32 v48, v48, v49
	v_cvt_pk_bf16_f32 v49, v50, v51
	v_cvt_pk_bf16_f32 v50, v52, v53
	v_cvt_pk_bf16_f32 v51, v54, v55
	v_cvt_pk_bf16_f32 v56, v56, v57
	v_cvt_pk_bf16_f32 v57, v58, v59
	v_cvt_pk_bf16_f32 v58, v60, v61
	v_cvt_pk_bf16_f32 v59, v62, v63
	v_cvt_pk_bf16_f32 v64, v64, v65
	v_cvt_pk_bf16_f32 v65, v66, v67
	v_cvt_pk_bf16_f32 v66, v68, v69
	v_cvt_pk_bf16_f32 v67, v70, v71
	s_nop 1
	s_setprio 1
	s_waitcnt lgkmcnt(10)
	v_mfma_f32_16x16x32_bf16 v[36:39], v[220:223], v[40:43], v[36:39]
	ds_read_b64_tr_b16 v[220:221], v241 offset:4672
	ds_read_b64_tr_b16 v[222:223], v241 offset:6976
	s_waitcnt lgkmcnt(10)
	v_mfma_f32_16x16x32_bf16 v[32:35], v[224:227], v[40:43], v[32:35]
	ds_read_b64_tr_b16 v[224:225], v241 offset:4704
	ds_read_b64_tr_b16 v[226:227], v241 offset:7008
	s_waitcnt lgkmcnt(10)
	v_mfma_f32_16x16x32_bf16 v[28:31], v[228:231], v[40:43], v[28:31]
	ds_read_b64_tr_b16 v[228:229], v241 offset:9216
	ds_read_b64_tr_b16 v[230:231], v241 offset:11520
	s_waitcnt lgkmcnt(10)
	v_mfma_f32_16x16x32_bf16 v[24:27], v[232:235], v[40:43], v[24:27]
	ds_read_b64_tr_b16 v[232:233], v241 offset:9248
	ds_read_b64_tr_b16 v[234:235], v241 offset:11552
	s_waitcnt lgkmcnt(10)
	v_mfma_f32_16x16x32_bf16 v[36:39], v[236:239], v[48:51], v[36:39]
	ds_read_b64_tr_b16 v[236:237], v241 offset:9280
	ds_read_b64_tr_b16 v[238:239], v241 offset:11584
	s_waitcnt lgkmcnt(10)
	v_mfma_f32_16x16x32_bf16 v[32:35], v[252:255], v[48:51], v[32:35]
	ds_read_b64_tr_b16 v[252:253], v241 offset:9312
	ds_read_b64_tr_b16 v[254:255], v241 offset:11616
	s_waitcnt lgkmcnt(10)
	v_mfma_f32_16x16x32_bf16 v[28:31], v[220:223], v[48:51], v[28:31]
	ds_read_b64_tr_b16 v[220:221], v241 offset:13824
	ds_read_b64_tr_b16 v[222:223], v241 offset:16128
	s_waitcnt lgkmcnt(10)
	v_mfma_f32_16x16x32_bf16 v[24:27], v[224:227], v[48:51], v[24:27]
	ds_read_b64_tr_b16 v[224:225], v241 offset:13856
	ds_read_b64_tr_b16 v[226:227], v241 offset:16160
	s_waitcnt lgkmcnt(10)
	v_mfma_f32_16x16x32_bf16 v[36:39], v[228:231], v[56:59], v[36:39]
	ds_read_b64_tr_b16 v[228:229], v241 offset:13888
	ds_read_b64_tr_b16 v[230:231], v241 offset:16192
	s_waitcnt lgkmcnt(10)
	v_mfma_f32_16x16x32_bf16 v[32:35], v[232:235], v[56:59], v[32:35]
	ds_read_b64_tr_b16 v[232:233], v241 offset:13920
	ds_read_b64_tr_b16 v[234:235], v241 offset:16224
	s_waitcnt lgkmcnt(10)
	v_mfma_f32_16x16x32_bf16 v[28:31], v[236:239], v[56:59], v[28:31]
	s_waitcnt lgkmcnt(8)
	v_mfma_f32_16x16x32_bf16 v[24:27], v[252:255], v[56:59], v[24:27]
	s_waitcnt lgkmcnt(6)
	v_mfma_f32_16x16x32_bf16 v[36:39], v[220:223], v[64:67], v[36:39]
	s_waitcnt lgkmcnt(4)
	v_mfma_f32_16x16x32_bf16 v[32:35], v[224:227], v[64:67], v[32:35]
	s_waitcnt lgkmcnt(2)
	v_mfma_f32_16x16x32_bf16 v[28:31], v[228:231], v[64:67], v[28:31]
	s_waitcnt lgkmcnt(0)
	v_mfma_f32_16x16x32_bf16 v[24:27], v[232:235], v[64:67], v[24:27]
	s_setprio 0
	s_nop 7
	s_branch .LBB0_1170
